# P6 layer-0: nt loads for the read-once Y and f32 x rows (on top of nt prologue / requant streams)
# speedup vs baseline: 1.0156x; 1.0017x over previous
; #define GAS __attribute__((address_space(1)))
; __device__ __forceinline__ void unpack8(v4u w, float (&f)[8]) { f[0] = bflo(w.x); f[1] = bfhi(w.x); f[2] = bflo(w.y); f[3] = bfhi(w.y); f[4] = bflo(w.z); f[5] = bfhi(w.z); f[6] = bflo(w.w); f[7] = bfhi(w.w); }
; template <bool XF32, bool FINAL, bool QUANT = false> ...
;     v4u yraw[8]; f32x4 xf[8][2]; v4u xr[8]; float s = 0.f; float am = 0.f;
; #pragma unroll
;     for (int j = 0; j < 8; ++j) yraw[j] = *(const GAS v4u*)(yrow + 8 * lane + 512 * j);
; #pragma unroll
;     for (int j = 0; j < 8; ++j) {
;         if (XF32) { xf[j][0] = *(const GAS f32x4*)((const float*)xrow + 8 * lane + 512 * j); xf[j][1] = *(const GAS f32x4*)((const float*)xrow + 8 * lane + 512 * j + 4); }
;         else xr[j] = *(const GAS v4u*)((const bf16*)xrow + 8 * lane + 512 * j); }
; #pragma unroll
;     for (int j = 0; j < 8; ++j) { float yf[8]; unpack8(yraw[j], yf);
; #pragma unroll
;         for (int e = 0; e < 8; ++e) s += yf[e] * yf[e]; }
;     const float rstd = 1.0f / sqrtf(wave_sum(s, lane) * (1.0f / DM) + eps_y);
.LBB0_644:
	v_lshl_add_u64 v[102:103], s[38:39], 0, v[96:97]
	v_add_co_u32_e32 v2, vcc, 0x3d200000, v102
	s_movk_i32 s8, 0xc7f0
	s_nop 0
	v_addc_co_u32_e32 v3, vcc, 0, v103, vcc
	v_add_co_u32_e32 v58, vcc, s52, v102
	global_load_dwordx4 v[108:111], v[2:3], off nt
	global_load_dwordx4 v[66:69], v[2:3], off offset:1024 nt
	global_load_dwordx4 v[38:41], v[2:3], off offset:2048 nt
	v_addc_co_u32_e32 v59, vcc, 0, v103, vcc
	global_load_dwordx4 v[10:13], v[58:59], off offset:3072 nt
	global_load_dwordx4 v[14:17], v[2:3], off offset:3072 nt
	global_load_dwordx4 v[34:37], v[58:59], off nt
	s_mov_b32 s9, -1
	v_lshl_add_u64 v[60:61], v[100:101], 0, s[8:9]
	s_movk_i32 s8, 0xcff0
	s_mov_b32 s9, -1
	v_lshl_add_u64 v[62:63], v[100:101], 0, s[8:9]
	s_movk_i32 s8, 0xd7f0
	s_mov_b32 s9, -1
	v_lshl_add_u64 v[2:3], v[100:101], 0, s[8:9]
	s_movk_i32 s8, 0xdff0
	s_movk_i32 s3, 0xe000
	s_mov_b32 s9, -1
	v_add_co_u32_e32 v4, vcc, s3, v100
	v_lshl_add_u64 v[6:7], v[100:101], 0, s[8:9]
	s_movk_i32 s8, 0xe7f0
	v_addc_co_u32_e32 v5, vcc, -1, v101, vcc
	s_mov_b32 s9, -1
	s_movk_i32 s3, 0xf000
	v_lshl_add_u64 v[8:9], v[100:101], 0, s[8:9]
	v_add_co_u32_e32 v104, vcc, s3, v100
	s_movk_i32 s3, 0xd000
	s_nop 0
	v_addc_co_u32_e32 v105, vcc, -1, v101, vcc
	global_load_dwordx4 v[50:53], v[82:83], off offset:16
	global_load_dwordx4 v[54:57], v[82:83], off
	global_load_dwordx4 v[42:45], v[82:83], off offset:2064
	global_load_dwordx4 v[46:49], v[82:83], off offset:2048
	global_load_dwordx4 v[30:33], v[4:5], off offset:-2064 nt
	global_load_dwordx4 v[26:29], v[2:3], off offset:16 nt
	global_load_dwordx4 v[70:73], v[58:59], off offset:1024 nt
	global_load_dwordx4 v[22:25], v[4:5], off offset:-16 nt
	global_load_dwordx4 v[18:21], v[6:7], off offset:16 nt
	s_nop 0
	global_load_dwordx4 v[2:5], v[104:105], off offset:-2064 nt
	s_nop 0
	global_load_dwordx4 v[6:9], v[8:9], off offset:16 nt
	v_add_co_u32_e32 v64, vcc, s3, v100
	global_load_dwordx4 v[148:151], v[58:59], off offset:2048 nt
	s_nop 0
	v_addc_co_u32_e32 v65, vcc, -1, v101, vcc
	global_load_dwordx4 v[74:77], v[64:65], off offset:-2064 nt
	global_load_dwordx4 v[78:81], v[60:61], off offset:16 nt
	s_nop 0
	global_load_dwordx4 v[58:61], v[64:65], off offset:-16 nt
	s_nop 0
	global_load_dwordx4 v[62:65], v[62:63], off offset:16 nt
	s_waitcnt vmcnt(21)
	v_and_b32_e32 v172, 0xffff0000, v108
	v_lshlrev_b32_e32 v173, 16, v109
	v_lshlrev_b32_e32 v108, 16, v108
	v_and_b32_e32 v109, 0xffff0000, v109
	s_waitcnt vmcnt(19)
	v_and_b32_e32 v106, 0xffff0000, v38
	v_lshlrev_b32_e32 v107, 16, v39
	v_lshlrev_b32_e32 v112, 16, v38
	v_and_b32_e32 v113, 0xffff0000, v39
	s_waitcnt vmcnt(18)
	v_lshlrev_b32_e32 v138, 16, v12
	v_and_b32_e32 v140, 0xffff0000, v12
	v_and_b32_e32 v142, 0xffff0000, v13
	v_lshlrev_b32_e32 v143, 16, v13
	v_pk_mul_f32 v[12:13], v[108:109], v[108:109]
	v_pk_mul_f32 v[38:39], v[172:173], v[172:173]
	v_lshlrev_b32_e32 v170, 16, v110
	v_add_f32_e32 v1, v12, v38
	v_and_b32_e32 v171, 0xffff0000, v111
	v_add_f32_e32 v1, v39, v1
	v_and_b32_e32 v174, 0xffff0000, v110
	v_lshlrev_b32_e32 v175, 16, v111
	v_and_b32_e32 v116, 0xffff0000, v66
	v_lshlrev_b32_e32 v117, 16, v67
	v_lshlrev_b32_e32 v110, 16, v66
	v_and_b32_e32 v111, 0xffff0000, v67
	v_pk_mul_f32 v[66:67], v[170:171], v[170:171]
	v_add_f32_e32 v1, v13, v1
	v_and_b32_e32 v166, 0xffff0000, v68
	v_lshlrev_b32_e32 v167, 16, v69
	v_lshlrev_b32_e32 v164, 16, v68
	v_and_b32_e32 v165, 0xffff0000, v69
	v_pk_mul_f32 v[68:69], v[174:175], v[174:175]
	v_add_f32_e32 v1, v66, v1
	v_add_f32_e32 v1, v68, v1
	v_add_f32_e32 v1, v69, v1
	v_pk_mul_f32 v[182:183], v[110:111], v[110:111]
	v_add_f32_e32 v1, v67, v1
	v_pk_mul_f32 v[184:185], v[116:117], v[116:117]
	v_add_f32_e32 v1, v182, v1
	v_add_f32_e32 v1, v184, v1
	v_add_f32_e32 v1, v185, v1
	v_pk_mul_f32 v[194:195], v[164:165], v[164:165]
	v_add_f32_e32 v1, v183, v1
	v_pk_mul_f32 v[196:197], v[166:167], v[166:167]
	v_add_f32_e32 v1, v194, v1
	v_add_f32_e32 v1, v196, v1
	v_add_f32_e32 v1, v197, v1
	v_pk_mul_f32 v[198:199], v[112:113], v[112:113]
	v_add_f32_e32 v1, v195, v1
	v_pk_mul_f32 v[200:201], v[106:107], v[106:107]
	v_add_f32_e32 v1, v198, v1
	v_add_f32_e32 v1, v200, v1
	v_lshlrev_b32_e32 v168, 16, v40
	v_and_b32_e32 v169, 0xffff0000, v41
	v_add_f32_e32 v1, v201, v1
	v_and_b32_e32 v162, 0xffff0000, v40
	v_lshlrev_b32_e32 v163, 16, v41
	v_pk_mul_f32 v[40:41], v[168:169], v[168:169]
	v_add_f32_e32 v1, v199, v1
	v_pk_mul_f32 v[216:217], v[162:163], v[162:163]
	v_add_f32_e32 v1, v40, v1
	v_add_f32_e32 v1, v216, v1
	s_waitcnt vmcnt(17)
	v_lshlrev_b32_e32 v122, 16, v14
	v_and_b32_e32 v123, 0xffff0000, v15
	v_add_f32_e32 v1, v217, v1
	v_and_b32_e32 v118, 0xffff0000, v14
	v_lshlrev_b32_e32 v119, 16, v15
	v_pk_mul_f32 v[14:15], v[122:123], v[122:123]
	v_add_f32_e32 v1, v41, v1
	v_pk_mul_f32 v[218:219], v[118:119], v[118:119]
	v_add_f32_e32 v1, v14, v1
	v_add_f32_e32 v1, v218, v1
	v_lshlrev_b32_e32 v124, 16, v16
	v_and_b32_e32 v125, 0xffff0000, v17
	v_add_f32_e32 v1, v219, v1
	v_and_b32_e32 v120, 0xffff0000, v16
	v_lshlrev_b32_e32 v121, 16, v17
	v_pk_mul_f32 v[16:17], v[124:125], v[124:125]
	v_add_f32_e32 v1, v15, v1
	v_pk_mul_f32 v[220:221], v[120:121], v[120:121]
	v_add_f32_e32 v1, v16, v1
	v_add_f32_e32 v1, v220, v1
	s_waitcnt vmcnt(16)
	v_lshlrev_b32_e32 v126, 16, v34
	v_and_b32_e32 v127, 0xffff0000, v35
	v_add_f32_e32 v1, v221, v1
	v_and_b32_e32 v128, 0xffff0000, v34
	v_lshlrev_b32_e32 v129, 16, v35
	v_pk_mul_f32 v[34:35], v[126:127], v[126:127]
	v_add_f32_e32 v1, v17, v1
	v_pk_mul_f32 v[222:223], v[128:129], v[128:129]
	v_add_f32_e32 v1, v34, v1
	v_add_f32_e32 v1, v222, v1
	v_lshlrev_b32_e32 v130, 16, v36
	v_and_b32_e32 v131, 0xffff0000, v37
	v_add_f32_e32 v1, v223, v1
	v_and_b32_e32 v132, 0xffff0000, v36
	v_lshlrev_b32_e32 v133, 16, v37
	v_pk_mul_f32 v[36:37], v[130:131], v[130:131]
	v_add_f32_e32 v1, v35, v1
	v_pk_mul_f32 v[224:225], v[132:133], v[132:133]
	v_add_f32_e32 v1, v36, v1
	v_add_f32_e32 v1, v224, v1
	s_waitcnt vmcnt(9)
; #define GAS __attribute__((address_space(1)))
; __device__ __forceinline__ void unpack8(v4u w, float (&f)[8]) { f[0] = bflo(w.x); f[1] = bfhi(w.x); f[2] = bflo(w.y); f[3] = bfhi(w.y); f[4] = bflo(w.z); f[5] = bfhi(w.z); f[6] = bflo(w.w); f[7] = bfhi(w.w); }
; template <bool XF32, bool FINAL, bool QUANT = false> ...
;     ...
;     for (int j = 0; j < 8; ++j) { float yf[8]; unpack8(yraw[j], yf);
; #pragma unroll
;         for (int e = 0; e < 8; ++e) s += yf[e] * yf[e]; }
;     const float rstd = 1.0f / sqrtf(wave_sum(s, lane) * (1.0f / DM) + eps_y);
;     float s2 = 0.f;
; #pragma unroll
;     for (int j = 0; j < 8; ++j) { const int c = 8 * lane + 512 * j; float yf[8], x[8]; unpack8(yraw[j], yf);
;         if (XF32) { x[0] = xf[j][0].x; x[1] = xf[j][0].y; x[2] = xf[j][0].z; x[3] = xf[j][0].w; x[4] = xf[j][1].x; x[5] = xf[j][1].y; x[6] = xf[j][1].z; x[7] = xf[j][1].w; }
;         else unpack8(xr[j], x);
;         const f32x4 g0 = *(const GAS f32x4*)(gpost + c), g1 = *(const GAS f32x4*)(gpost + c + 4);
; #pragma unroll
;         for (int e = 0; e < 4; ++e) { x[e] += yf[e] * rstd * g0[e]; x[4 + e] += yf[4 + e] * rstd * g1[e]; }
	v_lshlrev_b32_e32 v134, 16, v70
	v_and_b32_e32 v135, 0xffff0000, v71
	v_add_f32_e32 v1, v225, v1
	v_and_b32_e32 v136, 0xffff0000, v70
	v_lshlrev_b32_e32 v137, 16, v71
	v_pk_mul_f32 v[70:71], v[134:135], v[134:135]
	v_add_f32_e32 v1, v37, v1
	v_pk_mul_f32 v[226:227], v[136:137], v[136:137]
	v_add_f32_e32 v1, v70, v1
	v_add_f32_e32 v1, v226, v1
	v_lshlrev_b32_e32 v156, 16, v72
	v_and_b32_e32 v157, 0xffff0000, v73
	v_add_f32_e32 v1, v227, v1
	v_and_b32_e32 v158, 0xffff0000, v72
	v_lshlrev_b32_e32 v159, 16, v73
	v_pk_mul_f32 v[72:73], v[156:157], v[156:157]
	v_add_f32_e32 v1, v71, v1
	v_pk_mul_f32 v[228:229], v[158:159], v[158:159]
	v_add_f32_e32 v1, v72, v1
	v_add_f32_e32 v1, v228, v1
	s_waitcnt vmcnt(4)
	v_lshlrev_b32_e32 v146, 16, v148
	v_and_b32_e32 v147, 0xffff0000, v149
	v_add_f32_e32 v1, v229, v1
	v_and_b32_e32 v144, 0xffff0000, v148
	v_lshlrev_b32_e32 v145, 16, v149
	v_pk_mul_f32 v[230:231], v[146:147], v[146:147]
	v_add_f32_e32 v1, v73, v1
	v_pk_mul_f32 v[232:233], v[144:145], v[144:145]
	v_add_f32_e32 v1, v230, v1
	v_add_f32_e32 v1, v232, v1
	v_and_b32_e32 v148, 0xffff0000, v150
	v_lshlrev_b32_e32 v149, 16, v151
	v_lshlrev_b32_e32 v150, 16, v150
	v_and_b32_e32 v151, 0xffff0000, v151
	v_add_f32_e32 v1, v233, v1
	v_pk_mul_f32 v[234:235], v[150:151], v[150:151]
	v_add_f32_e32 v1, v231, v1
	v_pk_mul_f32 v[236:237], v[148:149], v[148:149]
	v_add_f32_e32 v1, v234, v1
	v_add_f32_e32 v1, v236, v1
	v_lshlrev_b32_e32 v154, 16, v10
	v_and_b32_e32 v155, 0xffff0000, v11
	v_add_f32_e32 v1, v237, v1
	v_and_b32_e32 v152, 0xffff0000, v10
	v_lshlrev_b32_e32 v153, 16, v11
	v_pk_mul_f32 v[10:11], v[154:155], v[154:155]
	v_add_f32_e32 v1, v235, v1
	v_pk_mul_f32 v[238:239], v[152:153], v[152:153]
	v_add_f32_e32 v1, v10, v1
	v_add_f32_e32 v1, v238, v1
	v_add_f32_e32 v1, v239, v1
	v_add_f32_e32 v1, v11, v1
	v_fmac_f32_e32 v1, v138, v138
	v_pk_mul_f32 v[214:215], v[142:143], v[142:143]
	v_fmac_f32_e32 v1, v140, v140
	v_add_f32_e32 v1, v215, v1
	v_add_f32_e32 v1, v214, v1
	ds_bpermute_b32 v10, v161, v1
	global_load_dwordx4 v[66:69], v[104:105], off offset:-16
	global_load_dwordx4 v[70:73], v[100:101], off offset:-4096
	global_load_dwordx4 v[34:37], v[100:101], off offset:-2048
	global_load_dwordx4 v[38:41], v[100:101], off offset:-2064
	v_mov_b32_e32 v105, v56
	v_mov_b32_e32 v104, v55
	v_mov_b32_e32 v55, v57
	s_waitcnt lgkmcnt(0)
	v_add_f32_e32 v1, v1, v10
	ds_bpermute_b32 v115, v176, v1
	v_mov_b32_e32 v57, v52
	v_mov_b32_e32 v185, v48
	v_mov_b32_e32 v196, v43
	v_mov_b32_e32 v197, v44
	s_waitcnt lgkmcnt(0)
	v_add_f32_e32 v1, v1, v115
	ds_bpermute_b32 v56, v177, v1
	v_mov_b32_e32 v184, v47
	v_mov_b32_e32 v47, v49
	s_waitcnt vmcnt(7)
	v_mov_b32_e32 v182, v75
	v_mov_b32_e32 v183, v76
	s_waitcnt lgkmcnt(0)
	v_add_f32_e32 v1, v1, v56
	ds_bpermute_b32 v115, v178, v1
	v_mov_b32_e32 v75, v77
	v_mov_b32_e32 v56, v51
	s_waitcnt vmcnt(6)
	v_mov_b32_e32 v76, v79
	v_mov_b32_e32 v77, v80
	s_waitcnt lgkmcnt(0)
	v_add_f32_e32 v1, v1, v115
	ds_bpermute_b32 v52, v179, v1
	s_waitcnt vmcnt(5)
	v_mov_b32_e32 v194, v59
	v_mov_b32_e32 v195, v60
	v_mov_b32_e32 v59, v61
	s_waitcnt vmcnt(4)
	v_mov_b32_e32 v198, v63
	s_waitcnt lgkmcnt(0)
	v_add_f32_e32 v1, v1, v52
	ds_bpermute_b32 v48, v180, v1
	v_mov_b32_e32 v199, v64
	v_mov_b32_e32 v63, v65
	v_mov_b32_e32 v51, v53
	v_mov_b32_e32 v79, v81
	s_waitcnt lgkmcnt(0)
	v_add_f32_e32 v1, v1, v48
	v_fmamk_f32 v1, v1, 0x39800000, v204
	v_mul_f32_e32 v48, 0x4f800000, v1
	v_cmp_gt_f32_e32 vcc, s73, v1
	global_load_dwordx4 v[10:13], v[100:101], off
	global_load_dwordx4 v[14:17], v[100:101], off offset:-16
	v_cndmask_b32_e32 v1, v1, v48, vcc
	v_sqrt_f32_e32 v48, v1
	v_mov_b32_e32 v141, v143
	v_add_u32_e32 v43, -1, v48
	v_fma_f32 v44, -v43, v48, v1
	v_cmp_ge_f32_e64 s[44:45], 0, v44
	v_add_u32_e32 v44, 1, v48
	s_nop 0
	v_cndmask_b32_e64 v43, v48, v43, s[44:45]
	v_fma_f32 v48, -v44, v48, v1
	v_cmp_lt_f32_e64 s[44:45], 0, v48
	s_nop 1
	v_cndmask_b32_e64 v43, v43, v44, s[44:45]
	v_mul_f32_e32 v44, 0x37800000, v43
	v_cndmask_b32_e32 v43, v43, v44, vcc
	v_cmp_class_f32_e32 vcc, v1, v205
	s_nop 1
	v_cndmask_b32_e32 v1, v43, v1, vcc
	v_div_scale_f32 v44, s[8:9], v1, v1, 1.0
	v_rcp_f32_e32 v48, v44
	v_mov_b32_e32 v43, v45
	s_add_u32 s8, s38, s6
	s_addc_u32 s9, s39, s7
	v_fma_f32 v45, -v44, v48, 1.0
	v_fmac_f32_e32 v48, v45, v48
	v_div_scale_f32 v45, vcc, 1.0, v1, 1.0
	v_mul_f32_e32 v49, v45, v48
	v_fma_f32 v52, -v44, v49, v45
	v_fmac_f32_e32 v49, v52, v48
	v_fma_f32 v44, -v44, v49, v45
	v_div_fmas_f32 v44, v44, v48, v49
	v_div_fixup_f32 v160, v44, v1, 1.0
	v_pk_mul_f32 v[44:45], v[160:161], v[172:173] op_sel_hi:[0,1]
	v_pk_fma_f32 v[60:61], v[104:105], v[44:45], v[182:183]
	v_pk_mul_f32 v[44:45], v[160:161], v[174:175] op_sel_hi:[0,1]
	v_pk_fma_f32 v[64:65], v[56:57], v[44:45], v[76:77]
	v_pk_mul_f32 v[44:45], v[160:161], v[108:109] op_sel_hi:[0,1]
	v_pk_fma_f32 v[74:75], v[54:55], v[44:45], v[74:75]
	v_pk_mul_f32 v[44:45], v[160:161], v[170:171] op_sel_hi:[0,1]
	v_pk_fma_f32 v[76:77], v[50:51], v[44:45], v[78:79]
	v_and_b32_sdwa v1, v61, v203 dst_sel:DWORD dst_unused:UNUSED_PAD src0_sel:WORD_1 src1_sel:DWORD
	v_and_b32_sdwa v44, v60, v203 dst_sel:DWORD dst_unused:UNUSED_PAD src0_sel:WORD_1 src1_sel:DWORD
	v_add3_u32 v53, v61, v1, s14
	v_add3_u32 v1, v60, v44, s14
	v_and_b32_e32 v50, 0xffff0000, v1
	v_and_b32_sdwa v1, v75, v203 dst_sel:DWORD dst_unused:UNUSED_PAD src0_sel:WORD_1 src1_sel:DWORD
	v_and_b32_sdwa v44, v74, v203 dst_sel:DWORD dst_unused:UNUSED_PAD src0_sel:WORD_1 src1_sel:DWORD
	v_add3_u32 v1, v75, v1, s14
	v_add3_u32 v54, v74, v44, s14
	v_and_b32_e32 v51, 0xffff0000, v1
	v_and_b32_sdwa v1, v65, v203 dst_sel:DWORD dst_unused:UNUSED_PAD src0_sel:WORD_1 src1_sel:DWORD
; #define GAS __attribute__((address_space(1)))
; __device__ __forceinline__ void unpack8(v4u w, float (&f)[8]) { f[0] = bflo(w.x); f[1] = bfhi(w.x); f[2] = bflo(w.y); f[3] = bfhi(w.y); f[4] = bflo(w.z); f[5] = bfhi(w.z); f[6] = bflo(w.w); f[7] = bfhi(w.w); }
; __device__ __forceinline__ v4u pack8(const float (&o)[8]) { v4u w; w.x = pk2(o[0], o[1]); w.y = pk2(o[2], o[3]); w.z = pk2(o[4], o[5]); w.w = pk2(o[6], o[7]); return w; }
; template <bool XF32, bool FINAL, bool QUANT = false> ...
;     ...
;     for (int j = 0; j < 8; ++j) { const int c = 8 * lane + 512 * j; float yf[8], x[8]; unpack8(yraw[j], yf);
;         if (XF32) { x[0] = xf[j][0].x; x[1] = xf[j][0].y; x[2] = xf[j][0].z; x[3] = xf[j][0].w; x[4] = xf[j][1].x; x[5] = xf[j][1].y; x[6] = xf[j][1].z; x[7] = xf[j][1].w; }
;         else unpack8(xr[j], x);
;         const f32x4 g0 = *(const GAS f32x4*)(gpost + c), g1 = *(const GAS f32x4*)(gpost + c + 4);
; #pragma unroll
;         for (int e = 0; e < 4; ++e) { x[e] += yf[e] * rstd * g0[e]; x[4 + e] += yf[4 + e] * rstd * g1[e]; }
;         if (FINAL) { *(GAS f32x4*)(orow + c) = (f32x4){x[0], x[1], x[2], x[3]}; *(GAS f32x4*)(orow + c + 4) = (f32x4){x[4], x[5], x[6], x[7]}; }
;         else {
; #pragma unroll
;             for (int e = 0; e < 8; ++e) s2 += x[e] * x[e];
;             const v4u pw = pack8(x); *(GAS v4u*)(xbrow + c) = pw;
	v_and_b32_sdwa v44, v64, v203 dst_sel:DWORD dst_unused:UNUSED_PAD src0_sel:WORD_1 src1_sel:DWORD
	v_add3_u32 v55, v65, v1, s14
	v_add3_u32 v1, v64, v44, s14
	v_and_b32_e32 v48, 0xffff0000, v1
	v_and_b32_sdwa v1, v77, v203 dst_sel:DWORD dst_unused:UNUSED_PAD src0_sel:WORD_1 src1_sel:DWORD
	v_add_co_u32_e32 v174, vcc, s46, v102
	v_and_b32_sdwa v44, v76, v203 dst_sel:DWORD dst_unused:UNUSED_PAD src0_sel:WORD_1 src1_sel:DWORD
	v_add3_u32 v1, v77, v1, s14
	v_addc_co_u32_e32 v175, vcc, 0, v103, vcc
	v_add3_u32 v56, v76, v44, s14
	v_and_b32_e32 v45, 0xffff0000, v1
	v_add_co_u32_e32 v108, vcc, s47, v102
	v_or_b32_sdwa v79, v51, v53 dst_sel:DWORD dst_unused:UNUSED_PAD src0_sel:DWORD src1_sel:WORD_1
	v_or_b32_sdwa v78, v54, v50 dst_sel:DWORD dst_unused:UNUSED_PAD src0_sel:WORD_1 src1_sel:DWORD
	v_or_b32_sdwa v81, v45, v55 dst_sel:DWORD dst_unused:UNUSED_PAD src0_sel:DWORD src1_sel:WORD_1
	v_or_b32_sdwa v80, v56, v48 dst_sel:DWORD dst_unused:UNUSED_PAD src0_sel:WORD_1 src1_sel:DWORD
	v_addc_co_u32_e32 v109, vcc, 0, v103, vcc
	global_store_dwordx4 v[108:109], v[78:81], off offset:-4096
	v_pk_mul_f32 v[102:103], v[160:161], v[110:111] op_sel_hi:[0,1]
	v_pk_fma_f32 v[102:103], v[46:47], v[102:103], v[58:59]
	v_pk_mul_f32 v[78:79], v[160:161], v[116:117] op_sel_hi:[0,1]
	v_pk_fma_f32 v[78:79], v[184:185], v[78:79], v[194:195]
	v_pk_mul_f32 v[46:47], v[160:161], v[164:165] op_sel_hi:[0,1]
	v_pk_fma_f32 v[104:105], v[42:43], v[46:47], v[62:63]
	v_and_b32_sdwa v1, v79, v203 dst_sel:DWORD dst_unused:UNUSED_PAD src0_sel:WORD_1 src1_sel:DWORD
	v_and_b32_sdwa v42, v78, v203 dst_sel:DWORD dst_unused:UNUSED_PAD src0_sel:WORD_1 src1_sel:DWORD
	v_add3_u32 v47, v79, v1, s14
	v_add3_u32 v1, v78, v42, s14
	v_pk_mul_f32 v[80:81], v[160:161], v[166:167] op_sel_hi:[0,1]
	v_and_b32_e32 v44, 0xffff0000, v1
	v_and_b32_sdwa v1, v103, v203 dst_sel:DWORD dst_unused:UNUSED_PAD src0_sel:WORD_1 src1_sel:DWORD
	v_pk_fma_f32 v[80:81], v[196:197], v[80:81], v[198:199]
	v_and_b32_sdwa v42, v102, v203 dst_sel:DWORD dst_unused:UNUSED_PAD src0_sel:WORD_1 src1_sel:DWORD
	v_add3_u32 v1, v103, v1, s14
	v_add3_u32 v46, v102, v42, s14
	v_and_b32_e32 v43, 0xffff0000, v1
	v_and_b32_sdwa v1, v81, v203 dst_sel:DWORD dst_unused:UNUSED_PAD src0_sel:WORD_1 src1_sel:DWORD
	v_and_b32_sdwa v42, v80, v203 dst_sel:DWORD dst_unused:UNUSED_PAD src0_sel:WORD_1 src1_sel:DWORD
	v_add3_u32 v49, v81, v1, s14
	v_add3_u32 v1, v80, v42, s14
	v_and_b32_e32 v42, 0xffff0000, v1
	v_and_b32_sdwa v1, v105, v203 dst_sel:DWORD dst_unused:UNUSED_PAD src0_sel:WORD_1 src1_sel:DWORD
	v_and_b32_sdwa v52, v104, v203 dst_sel:DWORD dst_unused:UNUSED_PAD src0_sel:WORD_1 src1_sel:DWORD
	v_add3_u32 v1, v105, v1, s14
	v_add3_u32 v52, v104, v52, s14
	v_and_b32_e32 v1, 0xffff0000, v1
	v_or_b32_sdwa v165, v43, v47 dst_sel:DWORD dst_unused:UNUSED_PAD src0_sel:DWORD src1_sel:WORD_1
	v_or_b32_sdwa v164, v46, v44 dst_sel:DWORD dst_unused:UNUSED_PAD src0_sel:WORD_1 src1_sel:DWORD
	v_or_b32_sdwa v167, v1, v49 dst_sel:DWORD dst_unused:UNUSED_PAD src0_sel:DWORD src1_sel:WORD_1
	v_or_b32_sdwa v166, v52, v42 dst_sel:DWORD dst_unused:UNUSED_PAD src0_sel:WORD_1 src1_sel:DWORD
	global_store_dwordx4 v[174:175], v[164:167], off offset:1024
	global_load_dwordx4 v[164:167], v[84:85], off
	global_load_dwordx4 v[170:173], v[84:85], off offset:16
	v_mov_b32_e32 v58, v31
	v_mov_b32_e32 v59, v32
	v_mov_b32_e32 v31, v33
	v_mov_b32_e32 v32, v27
	v_mov_b32_e32 v33, v28
	v_mov_b32_e32 v27, v29
	v_pk_mul_f32 v[28:29], v[160:161], v[106:107] op_sel_hi:[0,1]
	v_pk_mul_f32 v[130:131], v[160:161], v[130:131] op_sel_hi:[0,1]
	v_pk_mul_f32 v[156:157], v[160:161], v[156:157] op_sel_hi:[0,1]
	v_pk_mul_f32 v[184:185], v[74:75], v[74:75]
	v_pk_mul_f32 v[194:195], v[60:61], v[60:61]
	v_pk_mul_f32 v[196:197], v[76:77], v[76:77]
	v_pk_mul_f32 v[198:199], v[64:65], v[64:65]
	v_pk_mul_f32 v[154:155], v[160:161], v[154:155] op_sel_hi:[0,1]
	s_waitcnt vmcnt(1)
	v_mov_b32_e32 v62, v165
	v_mov_b32_e32 v63, v166
	v_pk_fma_f32 v[106:107], v[62:63], v[28:29], v[58:59]
	v_pk_mul_f32 v[28:29], v[160:161], v[162:163] op_sel_hi:[0,1]
	s_waitcnt vmcnt(0)
	v_mov_b32_e32 v58, v171
	v_mov_b32_e32 v59, v172
	v_pk_fma_f32 v[110:111], v[58:59], v[28:29], v[32:33]
	v_pk_mul_f32 v[28:29], v[160:161], v[112:113] op_sel_hi:[0,1]
	v_mov_b32_e32 v165, v167
	v_pk_fma_f32 v[112:113], v[164:165], v[28:29], v[30:31]
	v_pk_mul_f32 v[28:29], v[160:161], v[168:169] op_sel_hi:[0,1]
	v_mov_b32_e32 v171, v173
	v_pk_fma_f32 v[116:117], v[170:171], v[28:29], v[26:27]
	v_and_b32_sdwa v26, v107, v203 dst_sel:DWORD dst_unused:UNUSED_PAD src0_sel:WORD_1 src1_sel:DWORD
	v_and_b32_sdwa v27, v106, v203 dst_sel:DWORD dst_unused:UNUSED_PAD src0_sel:WORD_1 src1_sel:DWORD
	v_add3_u32 v31, v107, v26, s14
	v_add3_u32 v26, v106, v27, s14
	v_and_b32_e32 v28, 0xffff0000, v26
	v_and_b32_sdwa v26, v113, v203 dst_sel:DWORD dst_unused:UNUSED_PAD src0_sel:WORD_1 src1_sel:DWORD
	v_and_b32_sdwa v27, v112, v203 dst_sel:DWORD dst_unused:UNUSED_PAD src0_sel:WORD_1 src1_sel:DWORD
	v_add3_u32 v26, v113, v26, s14
	v_add3_u32 v30, v112, v27, s14
	v_and_b32_e32 v29, 0xffff0000, v26
	v_and_b32_sdwa v26, v111, v203 dst_sel:DWORD dst_unused:UNUSED_PAD src0_sel:WORD_1 src1_sel:DWORD
	v_and_b32_sdwa v27, v110, v203 dst_sel:DWORD dst_unused:UNUSED_PAD src0_sel:WORD_1 src1_sel:DWORD
	v_add3_u32 v33, v111, v26, s14
	v_add3_u32 v26, v110, v27, s14
	v_and_b32_sdwa v27, v117, v203 dst_sel:DWORD dst_unused:UNUSED_PAD src0_sel:WORD_1 src1_sel:DWORD
	v_and_b32_sdwa v32, v116, v203 dst_sel:DWORD dst_unused:UNUSED_PAD src0_sel:WORD_1 src1_sel:DWORD
	v_add3_u32 v27, v117, v27, s14
	v_and_b32_e32 v26, 0xffff0000, v26
	v_add3_u32 v32, v116, v32, s14
	v_and_b32_e32 v27, 0xffff0000, v27
	v_or_b32_sdwa v163, v29, v31 dst_sel:DWORD dst_unused:UNUSED_PAD src0_sel:DWORD src1_sel:WORD_1
	v_or_b32_sdwa v162, v30, v28 dst_sel:DWORD dst_unused:UNUSED_PAD src0_sel:WORD_1 src1_sel:DWORD
	v_or_b32_sdwa v165, v27, v33 dst_sel:DWORD dst_unused:UNUSED_PAD src0_sel:DWORD src1_sel:WORD_1
	v_or_b32_sdwa v164, v32, v26 dst_sel:DWORD dst_unused:UNUSED_PAD src0_sel:WORD_1 src1_sel:DWORD
	global_store_dwordx4 v[174:175], v[162:165], off offset:2048
	global_load_dwordx4 v[162:165], v[86:87], off
	s_nop 0
	global_load_dwordx4 v[166:169], v[86:87], off offset:16
	v_mov_b32_e32 v58, v23
	v_mov_b32_e32 v59, v24
	v_mov_b32_e32 v23, v25
	v_mov_b32_e32 v24, v19
	v_mov_b32_e32 v25, v20
	v_mov_b32_e32 v19, v21
	v_pk_mul_f32 v[20:21], v[160:161], v[118:119] op_sel_hi:[0,1]
	v_pk_mul_f32 v[172:173], v[160:161], v[152:153] op_sel_hi:[0,1]
	s_waitcnt vmcnt(1)
; #define GAS __attribute__((address_space(1)))
; __device__ __forceinline__ void unpack8(v4u w, float (&f)[8]) { f[0] = bflo(w.x); f[1] = bfhi(w.x); f[2] = bflo(w.y); f[3] = bfhi(w.y); f[4] = bflo(w.z); f[5] = bfhi(w.z); f[6] = bflo(w.w); f[7] = bfhi(w.w); }
; __device__ __forceinline__ v4u pack8(const float (&o)[8]) { v4u w; w.x = pk2(o[0], o[1]); w.y = pk2(o[2], o[3]); w.z = pk2(o[4], o[5]); w.w = pk2(o[6], o[7]); return w; }
; template <bool XF32, bool FINAL, bool QUANT = false> ...
;     ...
;     for (int j = 0; j < 8; ++j) { const int c = 8 * lane + 512 * j; float yf[8], x[8]; unpack8(yraw[j], yf);
;         if (XF32) { x[0] = xf[j][0].x; x[1] = xf[j][0].y; x[2] = xf[j][0].z; x[3] = xf[j][0].w; x[4] = xf[j][1].x; x[5] = xf[j][1].y; x[6] = xf[j][1].z; x[7] = xf[j][1].w; }
;         else unpack8(xr[j], x);
;         const f32x4 g0 = *(const GAS f32x4*)(gpost + c), g1 = *(const GAS f32x4*)(gpost + c + 4);
; #pragma unroll
;         for (int e = 0; e < 4; ++e) { x[e] += yf[e] * rstd * g0[e]; x[4 + e] += yf[4 + e] * rstd * g1[e]; }
;         if (FINAL) { *(GAS f32x4*)(orow + c) = (f32x4){x[0], x[1], x[2], x[3]}; *(GAS f32x4*)(orow + c + 4) = (f32x4){x[4], x[5], x[6], x[7]}; }
;         else {
; #pragma unroll
;             for (int e = 0; e < 8; ++e) s2 += x[e] * x[e];
;             const v4u pw = pack8(x); *(GAS v4u*)(xbrow + c) = pw;
	v_mov_b32_e32 v62, v163
	v_mov_b32_e32 v63, v164
	v_pk_fma_f32 v[118:119], v[62:63], v[20:21], v[58:59]
	v_pk_mul_f32 v[20:21], v[160:161], v[120:121] op_sel_hi:[0,1]
	s_waitcnt vmcnt(0)
	v_mov_b32_e32 v58, v167
	v_mov_b32_e32 v59, v168
	v_pk_fma_f32 v[120:121], v[58:59], v[20:21], v[24:25]
	v_pk_mul_f32 v[20:21], v[160:161], v[122:123] op_sel_hi:[0,1]
	v_mov_b32_e32 v163, v165
	v_pk_fma_f32 v[122:123], v[162:163], v[20:21], v[22:23]
	v_pk_mul_f32 v[20:21], v[160:161], v[124:125] op_sel_hi:[0,1]
	v_mov_b32_e32 v167, v169
	v_pk_fma_f32 v[124:125], v[166:167], v[20:21], v[18:19]
	v_and_b32_sdwa v18, v119, v203 dst_sel:DWORD dst_unused:UNUSED_PAD src0_sel:WORD_1 src1_sel:DWORD
	v_and_b32_sdwa v19, v118, v203 dst_sel:DWORD dst_unused:UNUSED_PAD src0_sel:WORD_1 src1_sel:DWORD
	v_add3_u32 v23, v119, v18, s14
	v_add3_u32 v18, v118, v19, s14
	v_and_b32_e32 v20, 0xffff0000, v18
	v_and_b32_sdwa v18, v123, v203 dst_sel:DWORD dst_unused:UNUSED_PAD src0_sel:WORD_1 src1_sel:DWORD
	v_and_b32_sdwa v19, v122, v203 dst_sel:DWORD dst_unused:UNUSED_PAD src0_sel:WORD_1 src1_sel:DWORD
	v_add3_u32 v18, v123, v18, s14
	v_add3_u32 v22, v122, v19, s14
	v_and_b32_e32 v21, 0xffff0000, v18
	v_and_b32_sdwa v18, v121, v203 dst_sel:DWORD dst_unused:UNUSED_PAD src0_sel:WORD_1 src1_sel:DWORD
	v_and_b32_sdwa v19, v120, v203 dst_sel:DWORD dst_unused:UNUSED_PAD src0_sel:WORD_1 src1_sel:DWORD
	v_add3_u32 v25, v121, v18, s14
	v_add3_u32 v18, v120, v19, s14
	v_and_b32_sdwa v19, v125, v203 dst_sel:DWORD dst_unused:UNUSED_PAD src0_sel:WORD_1 src1_sel:DWORD
	v_and_b32_sdwa v24, v124, v203 dst_sel:DWORD dst_unused:UNUSED_PAD src0_sel:WORD_1 src1_sel:DWORD
	v_add3_u32 v19, v125, v19, s14
	v_and_b32_e32 v18, 0xffff0000, v18
	v_add3_u32 v24, v124, v24, s14
	v_and_b32_e32 v19, 0xffff0000, v19
	v_or_b32_sdwa v163, v21, v23 dst_sel:DWORD dst_unused:UNUSED_PAD src0_sel:DWORD src1_sel:WORD_1
	v_or_b32_sdwa v162, v22, v20 dst_sel:DWORD dst_unused:UNUSED_PAD src0_sel:WORD_1 src1_sel:DWORD
	v_or_b32_sdwa v165, v19, v25 dst_sel:DWORD dst_unused:UNUSED_PAD src0_sel:DWORD src1_sel:WORD_1
	v_or_b32_sdwa v164, v24, v18 dst_sel:DWORD dst_unused:UNUSED_PAD src0_sel:WORD_1 src1_sel:DWORD
	global_store_dwordx4 v[174:175], v[162:165], off offset:3072
	global_load_dwordx4 v[162:165], v[88:89], off
	global_load_dwordx4 v[166:169], v[88:89], off offset:16
	v_mov_b32_e32 v58, v3
	v_mov_b32_e32 v59, v4
	v_mov_b32_e32 v3, v5
	v_mov_b32_e32 v4, v7
	v_mov_b32_e32 v5, v8
	v_mov_b32_e32 v7, v9
	v_pk_mul_f32 v[8:9], v[160:161], v[128:129] op_sel_hi:[0,1]
	v_pk_mul_f32 v[62:63], v[160:161], v[132:133] op_sel_hi:[0,1]
	v_pk_mul_f32 v[132:133], v[160:161], v[126:127] op_sel_hi:[0,1]
	v_pk_mul_f32 v[174:175], v[160:161], v[140:141] op_sel_hi:[0,1]
	s_waitcnt vmcnt(1)
	v_mov_b32_e32 v126, v163
	v_mov_b32_e32 v127, v164
	v_mov_b32_e32 v163, v165
	v_pk_fma_f32 v[128:129], v[126:127], v[8:9], v[58:59]
	s_waitcnt vmcnt(0)
	v_mov_b32_e32 v170, v167
	v_mov_b32_e32 v171, v168
	v_pk_fma_f32 v[132:133], v[162:163], v[132:133], v[2:3]
	v_and_b32_sdwa v2, v129, v203 dst_sel:DWORD dst_unused:UNUSED_PAD src0_sel:WORD_1 src1_sel:DWORD
	v_and_b32_sdwa v3, v128, v203 dst_sel:DWORD dst_unused:UNUSED_PAD src0_sel:WORD_1 src1_sel:DWORD
	v_pk_fma_f32 v[126:127], v[170:171], v[62:63], v[4:5]
	v_add3_u32 v5, v129, v2, s14
	v_add3_u32 v2, v128, v3, s14
	v_and_b32_e32 v4, 0xffff0000, v2
	v_and_b32_sdwa v2, v133, v203 dst_sel:DWORD dst_unused:UNUSED_PAD src0_sel:WORD_1 src1_sel:DWORD
	v_mov_b32_e32 v167, v169
	v_and_b32_sdwa v3, v132, v203 dst_sel:DWORD dst_unused:UNUSED_PAD src0_sel:WORD_1 src1_sel:DWORD
	v_add3_u32 v2, v133, v2, s14
	v_pk_fma_f32 v[130:131], v[166:167], v[130:131], v[6:7]
	v_add3_u32 v6, v132, v3, s14
	v_and_b32_e32 v7, 0xffff0000, v2
	v_and_b32_sdwa v2, v127, v203 dst_sel:DWORD dst_unused:UNUSED_PAD src0_sel:WORD_1 src1_sel:DWORD
	v_and_b32_sdwa v3, v126, v203 dst_sel:DWORD dst_unused:UNUSED_PAD src0_sel:WORD_1 src1_sel:DWORD
	v_add3_u32 v9, v127, v2, s14
	v_add3_u32 v2, v126, v3, s14
	v_and_b32_sdwa v3, v131, v203 dst_sel:DWORD dst_unused:UNUSED_PAD src0_sel:WORD_1 src1_sel:DWORD
	v_and_b32_sdwa v8, v130, v203 dst_sel:DWORD dst_unused:UNUSED_PAD src0_sel:WORD_1 src1_sel:DWORD
	v_add3_u32 v3, v131, v3, s14
	v_and_b32_e32 v2, 0xffff0000, v2
	v_add3_u32 v8, v130, v8, s14
	v_and_b32_e32 v3, 0xffff0000, v3
	v_or_b32_sdwa v163, v7, v5 dst_sel:DWORD dst_unused:UNUSED_PAD src0_sel:DWORD src1_sel:WORD_1
	v_or_b32_sdwa v162, v6, v4 dst_sel:DWORD dst_unused:UNUSED_PAD src0_sel:WORD_1 src1_sel:DWORD
	v_or_b32_sdwa v165, v3, v9 dst_sel:DWORD dst_unused:UNUSED_PAD src0_sel:DWORD src1_sel:WORD_1
	v_or_b32_sdwa v164, v8, v2 dst_sel:DWORD dst_unused:UNUSED_PAD src0_sel:WORD_1 src1_sel:DWORD
	global_store_dwordx4 v[108:109], v[162:165], off
	global_load_dwordx4 v[162:165], v[90:91], off
	s_nop 0
	global_load_dwordx4 v[166:169], v[90:91], off offset:16
	v_mov_b32_e32 v58, v67
	v_mov_b32_e32 v59, v68
	v_mov_b32_e32 v67, v69
	v_mov_b32_e32 v62, v71
	v_mov_b32_e32 v63, v72
	v_mov_b32_e32 v71, v73
	v_pk_mul_f32 v[68:69], v[160:161], v[136:137] op_sel_hi:[0,1]
	v_pk_mul_f32 v[72:73], v[160:161], v[158:159] op_sel_hi:[0,1]
	v_pk_mul_f32 v[136:137], v[160:161], v[134:135] op_sel_hi:[0,1]
	v_mov_b32_e32 v170, v11
	v_mov_b32_e32 v171, v12
	v_mov_b32_e32 v11, v13
	v_pk_mul_f32 v[12:13], v[160:161], v[144:145] op_sel_hi:[0,1]
	s_waitcnt vmcnt(1)
	v_mov_b32_e32 v134, v163
	v_mov_b32_e32 v135, v164
	s_waitcnt vmcnt(0)
; #define GAS __attribute__((address_space(1)))
; __device__ __forceinline__ void unpack8(v4u w, float (&f)[8]) { f[0] = bflo(w.x); f[1] = bfhi(w.x); f[2] = bflo(w.y); f[3] = bfhi(w.y); f[4] = bflo(w.z); f[5] = bfhi(w.z); f[6] = bflo(w.w); f[7] = bfhi(w.w); }
; __device__ __forceinline__ v4u pack8(const float (&o)[8]) { v4u w; w.x = pk2(o[0], o[1]); w.y = pk2(o[2], o[3]); w.z = pk2(o[4], o[5]); w.w = pk2(o[6], o[7]); return w; }
; template <bool XF32, bool FINAL, bool QUANT = false> ...
;     ...
;     for (int j = 0; j < 8; ++j) { const int c = 8 * lane + 512 * j; float yf[8], x[8]; unpack8(yraw[j], yf);
;         if (XF32) { x[0] = xf[j][0].x; x[1] = xf[j][0].y; x[2] = xf[j][0].z; x[3] = xf[j][0].w; x[4] = xf[j][1].x; x[5] = xf[j][1].y; x[6] = xf[j][1].z; x[7] = xf[j][1].w; }
;         else unpack8(xr[j], x);
;         const f32x4 g0 = *(const GAS f32x4*)(gpost + c), g1 = *(const GAS f32x4*)(gpost + c + 4);
; #pragma unroll
;         for (int e = 0; e < 4; ++e) { x[e] += yf[e] * rstd * g0[e]; x[4 + e] += yf[4 + e] * rstd * g1[e]; }
;         if (FINAL) { *(GAS f32x4*)(orow + c) = (f32x4){x[0], x[1], x[2], x[3]}; *(GAS f32x4*)(orow + c + 4) = (f32x4){x[4], x[5], x[6], x[7]}; }
;         else {
; #pragma unroll
;             for (int e = 0; e < 8; ++e) s2 += x[e] * x[e];
;             const v4u pw = pack8(x); *(GAS v4u*)(xbrow + c) = pw;
	v_mov_b32_e32 v158, v167
	v_mov_b32_e32 v159, v168
	v_mov_b32_e32 v163, v165
	v_mov_b32_e32 v167, v169
	v_pk_fma_f32 v[134:135], v[134:135], v[68:69], v[58:59]
	v_pk_fma_f32 v[72:73], v[158:159], v[72:73], v[62:63]
	v_pk_fma_f32 v[136:137], v[162:163], v[136:137], v[66:67]
	v_pk_fma_f32 v[70:71], v[166:167], v[156:157], v[70:71]
	v_and_b32_sdwa v57, v135, v203 dst_sel:DWORD dst_unused:UNUSED_PAD src0_sel:WORD_1 src1_sel:DWORD
	v_and_b32_sdwa v58, v134, v203 dst_sel:DWORD dst_unused:UNUSED_PAD src0_sel:WORD_1 src1_sel:DWORD
	v_and_b32_sdwa v59, v137, v203 dst_sel:DWORD dst_unused:UNUSED_PAD src0_sel:WORD_1 src1_sel:DWORD
	v_and_b32_sdwa v68, v72, v203 dst_sel:DWORD dst_unused:UNUSED_PAD src0_sel:WORD_1 src1_sel:DWORD
	v_and_b32_sdwa v69, v71, v203 dst_sel:DWORD dst_unused:UNUSED_PAD src0_sel:WORD_1 src1_sel:DWORD
	v_and_b32_sdwa v62, v136, v203 dst_sel:DWORD dst_unused:UNUSED_PAD src0_sel:WORD_1 src1_sel:DWORD
	v_and_b32_sdwa v67, v73, v203 dst_sel:DWORD dst_unused:UNUSED_PAD src0_sel:WORD_1 src1_sel:DWORD
	v_and_b32_sdwa v115, v70, v203 dst_sel:DWORD dst_unused:UNUSED_PAD src0_sel:WORD_1 src1_sel:DWORD
	v_add3_u32 v63, v135, v57, s14
	v_add3_u32 v57, v134, v58, s14
	v_add3_u32 v58, v137, v59, s14
	v_add3_u32 v139, v72, v68, s14
	v_add3_u32 v69, v71, v69, s14
	v_add3_u32 v66, v136, v62, s14
	v_add3_u32 v67, v73, v67, s14
	v_add3_u32 v68, v70, v115, s14
	v_and_b32_e32 v62, 0xffff0000, v57
	v_and_b32_e32 v59, 0xffff0000, v58
	v_and_b32_e32 v58, 0xffff0000, v139
	v_and_b32_e32 v57, 0xffff0000, v69
	v_or_b32_sdwa v157, v59, v63 dst_sel:DWORD dst_unused:UNUSED_PAD src0_sel:DWORD src1_sel:WORD_1
	v_or_b32_sdwa v156, v66, v62 dst_sel:DWORD dst_unused:UNUSED_PAD src0_sel:WORD_1 src1_sel:DWORD
	v_or_b32_sdwa v159, v57, v67 dst_sel:DWORD dst_unused:UNUSED_PAD src0_sel:DWORD src1_sel:WORD_1
	v_or_b32_sdwa v158, v68, v58 dst_sel:DWORD dst_unused:UNUSED_PAD src0_sel:WORD_1 src1_sel:DWORD
	global_store_dwordx4 v[108:109], v[156:159], off offset:1024
	global_load_dwordx4 v[156:159], v[92:93], off
	global_load_dwordx4 v[162:165], v[92:93], off offset:16
	v_mov_b32_e32 v139, v142
	v_mov_b32_e32 v166, v39
	v_mov_b32_e32 v167, v40
	v_mov_b32_e32 v39, v41
	v_mov_b32_e32 v40, v35
	v_mov_b32_e32 v41, v36
	v_mov_b32_e32 v35, v37
	v_mov_b32_e32 v168, v15
	v_mov_b32_e32 v169, v16
	v_mov_b32_e32 v15, v17
	v_pk_mul_f32 v[16:17], v[160:161], v[148:149] op_sel_hi:[0,1]
	v_pk_mul_f32 v[36:37], v[160:161], v[146:147] op_sel_hi:[0,1]
	v_pk_mul_f32 v[142:143], v[160:161], v[150:151] op_sel_hi:[0,1]
	v_pk_mul_f32 v[182:183], v[160:161], v[138:139] op_sel_hi:[0,1]
	s_waitcnt vmcnt(1)
	v_mov_b32_e32 v138, v157
	v_mov_b32_e32 v139, v158
	s_waitcnt vmcnt(0)
	v_mov_b32_e32 v140, v163
	v_mov_b32_e32 v141, v164
	v_mov_b32_e32 v157, v159
	v_mov_b32_e32 v163, v165
	v_pk_fma_f32 v[138:139], v[138:139], v[12:13], v[166:167]
	v_pk_fma_f32 v[40:41], v[140:141], v[16:17], v[40:41]
	v_pk_fma_f32 v[140:141], v[156:157], v[36:37], v[38:39]
	v_pk_fma_f32 v[38:39], v[162:163], v[142:143], v[34:35]
	v_and_b32_sdwa v12, v139, v203 dst_sel:DWORD dst_unused:UNUSED_PAD src0_sel:WORD_1 src1_sel:DWORD
	v_and_b32_sdwa v13, v138, v203 dst_sel:DWORD dst_unused:UNUSED_PAD src0_sel:WORD_1 src1_sel:DWORD
	v_and_b32_sdwa v16, v141, v203 dst_sel:DWORD dst_unused:UNUSED_PAD src0_sel:WORD_1 src1_sel:DWORD
	v_and_b32_sdwa v69, v40, v203 dst_sel:DWORD dst_unused:UNUSED_PAD src0_sel:WORD_1 src1_sel:DWORD
	v_and_b32_sdwa v115, v39, v203 dst_sel:DWORD dst_unused:UNUSED_PAD src0_sel:WORD_1 src1_sel:DWORD
	v_and_b32_sdwa v17, v140, v203 dst_sel:DWORD dst_unused:UNUSED_PAD src0_sel:WORD_1 src1_sel:DWORD
	v_and_b32_sdwa v36, v41, v203 dst_sel:DWORD dst_unused:UNUSED_PAD src0_sel:WORD_1 src1_sel:DWORD
	v_and_b32_sdwa v142, v38, v203 dst_sel:DWORD dst_unused:UNUSED_PAD src0_sel:WORD_1 src1_sel:DWORD
	v_add3_u32 v35, v139, v12, s14
	v_add3_u32 v12, v138, v13, s14
	v_add3_u32 v13, v141, v16, s14
	v_add3_u32 v69, v40, v69, s14
	v_add3_u32 v115, v39, v115, s14
	v_add3_u32 v34, v140, v17, s14
	v_add3_u32 v37, v41, v36, s14
	v_add3_u32 v36, v38, v142, s14
	v_and_b32_e32 v16, 0xffff0000, v12
	v_and_b32_e32 v17, 0xffff0000, v13
	v_and_b32_e32 v12, 0xffff0000, v69
	v_and_b32_e32 v13, 0xffff0000, v115
	v_or_b32_sdwa v143, v17, v35 dst_sel:DWORD dst_unused:UNUSED_PAD src0_sel:DWORD src1_sel:WORD_1
	v_or_b32_sdwa v142, v34, v16 dst_sel:DWORD dst_unused:UNUSED_PAD src0_sel:WORD_1 src1_sel:DWORD
	v_or_b32_sdwa v145, v13, v37 dst_sel:DWORD dst_unused:UNUSED_PAD src0_sel:DWORD src1_sel:WORD_1
	v_or_b32_sdwa v144, v36, v12 dst_sel:DWORD dst_unused:UNUSED_PAD src0_sel:WORD_1 src1_sel:DWORD
	global_store_dwordx4 v[108:109], v[142:145], off offset:2048
	global_load_dwordx4 v[146:149], v[94:95], off offset:16
	global_load_dwordx4 v[150:153], v[94:95], off
	v_add_f32_e32 v69, v184, v194
	v_add_f32_e32 v69, v195, v69
	v_add_f32_e32 v69, v185, v69
	v_add_f32_e32 v69, v196, v69
	v_add_f32_e32 v69, v198, v69
	v_add_f32_e32 v69, v199, v69
	v_pk_mul_f32 v[142:143], v[102:103], v[102:103]
	v_add_f32_e32 v69, v197, v69
	v_pk_mul_f32 v[144:145], v[78:79], v[78:79]
	v_add_f32_e32 v69, v142, v69
	v_add_f32_e32 v69, v144, v69
	v_add_f32_e32 v69, v145, v69
	v_pk_mul_f32 v[156:157], v[104:105], v[104:105]
	v_add_f32_e32 v69, v143, v69
	v_pk_mul_f32 v[158:159], v[80:81], v[80:81]
	v_add_f32_e32 v69, v156, v69
	v_add_f32_e32 v69, v158, v69
	v_add_f32_e32 v69, v159, v69
	v_add_f32_e32 v69, v157, v69
	v_pk_mul_f32 v[142:143], v[112:113], v[112:113]
	v_pk_mul_f32 v[144:145], v[106:107], v[106:107]
	v_add_f32_e32 v69, v142, v69
	v_add_f32_e32 v69, v144, v69
	v_add_f32_e32 v69, v145, v69
	v_pk_mul_f32 v[156:157], v[116:117], v[116:117]
	v_add_f32_e32 v69, v143, v69
; #define GAS __attribute__((address_space(1)))
; __device__ __forceinline__ v4u pack8(const float (&o)[8]) { v4u w; w.x = pk2(o[0], o[1]); w.y = pk2(o[2], o[3]); w.z = pk2(o[4], o[5]); w.w = pk2(o[6], o[7]); return w; }
; template <bool XF32, bool FINAL, bool QUANT = false> ...
;     ...
;             for (int e = 0; e < 8; ++e) s2 += x[e] * x[e];
;             const v4u pw = pack8(x); *(GAS v4u*)(xbrow + c) = pw;
;             if (QUANT) { xr[j] = pw;
; #pragma unroll
;                 for (int e = 0; e < 8; ++e) am = fmaxf(am, fabsf(x[e])); } }
;         if (j & 1) asm volatile("" ::: "memory"); }
;     if (!FINAL) { const float tot = wave_sum(s2, lane); const float rsn = 1.0f / sqrtf(tot * (1.0f / DM) + EPS); if (lane == 0) *rs_out = rsn;
	v_pk_mul_f32 v[158:159], v[110:111], v[110:111]
	v_add_f32_e32 v69, v156, v69
	v_add_f32_e32 v69, v158, v69
	v_add_f32_e32 v69, v159, v69
	v_add_f32_e32 v69, v157, v69
	v_pk_mul_f32 v[142:143], v[122:123], v[122:123]
	v_pk_mul_f32 v[144:145], v[118:119], v[118:119]
	v_add_f32_e32 v69, v142, v69
	v_add_f32_e32 v69, v144, v69
	v_add_f32_e32 v69, v145, v69
	v_pk_mul_f32 v[156:157], v[124:125], v[124:125]
	v_add_f32_e32 v69, v143, v69
	v_pk_mul_f32 v[158:159], v[120:121], v[120:121]
	v_add_f32_e32 v69, v156, v69
	v_add_f32_e32 v69, v158, v69
	v_add_f32_e32 v69, v159, v69
	v_add_f32_e32 v69, v157, v69
	v_pk_mul_f32 v[142:143], v[132:133], v[132:133]
	v_pk_mul_f32 v[144:145], v[128:129], v[128:129]
	v_add_f32_e32 v69, v142, v69
	v_add_f32_e32 v69, v144, v69
	v_add_f32_e32 v69, v145, v69
	v_pk_mul_f32 v[156:157], v[130:131], v[130:131]
	v_add_f32_e32 v69, v143, v69
	v_pk_mul_f32 v[158:159], v[126:127], v[126:127]
	v_add_f32_e32 v69, v156, v69
	v_add_f32_e32 v69, v158, v69
	v_add_f32_e32 v69, v159, v69
	v_add_f32_e32 v69, v157, v69
	v_pk_mul_f32 v[142:143], v[136:137], v[136:137]
	v_pk_mul_f32 v[144:145], v[134:135], v[134:135]
	v_add_f32_e32 v69, v142, v69
	v_add_f32_e32 v69, v144, v69
	v_add_f32_e32 v69, v145, v69
	v_pk_mul_f32 v[156:157], v[70:71], v[70:71]
	v_add_f32_e32 v69, v143, v69
	v_pk_mul_f32 v[158:159], v[72:73], v[72:73]
	v_add_f32_e32 v69, v156, v69
	v_add_f32_e32 v69, v158, v69
	v_add_f32_e32 v69, v159, v69
	v_add_f32_e32 v69, v157, v69
	v_pk_mul_f32 v[142:143], v[140:141], v[140:141]
	v_pk_mul_f32 v[144:145], v[138:139], v[138:139]
	v_add_f32_e32 v69, v142, v69
	v_add_f32_e32 v69, v144, v69
	v_add_f32_e32 v69, v145, v69
	v_pk_mul_f32 v[156:157], v[38:39], v[38:39]
	v_add_f32_e32 v69, v143, v69
	v_pk_mul_f32 v[158:159], v[40:41], v[40:41]
	v_add_f32_e32 v69, v156, v69
	v_add_f32_e32 v69, v158, v69
	v_add_f32_e32 v69, v159, v69
	v_add_f32_e32 v69, v157, v69
	s_waitcnt vmcnt(0)
	v_mov_b32_e32 v142, v151
	v_mov_b32_e32 v151, v153
	v_mov_b32_e32 v143, v152
	v_mov_b32_e32 v152, v147
	v_mov_b32_e32 v147, v149
	v_pk_fma_f32 v[144:145], v[150:151], v[154:155], v[14:15]
	v_pk_fma_f32 v[142:143], v[142:143], v[172:173], v[168:169]
	v_pk_fma_f32 v[10:11], v[146:147], v[182:183], v[10:11]
	v_pk_mul_f32 v[146:147], v[144:145], v[144:145]
	v_mov_b32_e32 v153, v148
	v_pk_mul_f32 v[148:149], v[142:143], v[142:143]
	v_add_f32_e32 v69, v146, v69
	v_add_f32_e32 v69, v148, v69
	v_add_f32_e32 v69, v149, v69
	v_pk_fma_f32 v[14:15], v[152:153], v[174:175], v[170:171]
	v_pk_mul_f32 v[150:151], v[10:11], v[10:11]
	v_add_f32_e32 v69, v147, v69
	v_pk_mul_f32 v[152:153], v[14:15], v[14:15]
	v_add_f32_e32 v69, v150, v69
	v_add_f32_e32 v69, v152, v69
	v_add_f32_e32 v69, v153, v69
	v_add_f32_e32 v69, v151, v69
	ds_bpermute_b32 v115, v161, v69
	v_and_b32_sdwa v146, v143, v203 dst_sel:DWORD dst_unused:UNUSED_PAD src0_sel:WORD_1 src1_sel:DWORD
	v_and_b32_sdwa v147, v142, v203 dst_sel:DWORD dst_unused:UNUSED_PAD src0_sel:WORD_1 src1_sel:DWORD
	v_and_b32_sdwa v151, v14, v203 dst_sel:DWORD dst_unused:UNUSED_PAD src0_sel:WORD_1 src1_sel:DWORD
	v_and_b32_sdwa v148, v145, v203 dst_sel:DWORD dst_unused:UNUSED_PAD src0_sel:WORD_1 src1_sel:DWORD
	s_waitcnt lgkmcnt(0)
	v_add_f32_e32 v69, v69, v115
	ds_bpermute_b32 v115, v176, v69
	v_and_b32_sdwa v149, v144, v203 dst_sel:DWORD dst_unused:UNUSED_PAD src0_sel:WORD_1 src1_sel:DWORD
	v_and_b32_sdwa v150, v15, v203 dst_sel:DWORD dst_unused:UNUSED_PAD src0_sel:WORD_1 src1_sel:DWORD
	v_add3_u32 v151, v14, v151, s14
	v_and_b32_sdwa v153, v11, v203 dst_sel:DWORD dst_unused:UNUSED_PAD src0_sel:WORD_1 src1_sel:DWORD
	s_waitcnt lgkmcnt(0)
	v_add_f32_e32 v69, v69, v115
	ds_bpermute_b32 v152, v177, v69
	v_add3_u32 v115, v143, v146, s14
	v_add3_u32 v146, v142, v147, s14
	v_add3_u32 v155, v145, v148, s14
	v_add3_u32 v148, v144, v149, s14
	s_waitcnt lgkmcnt(0)
	v_add_f32_e32 v69, v69, v152
	ds_bpermute_b32 v147, v178, v69
	v_add3_u32 v149, v15, v150, s14
	v_and_b32_e32 v150, 0xffff0000, v146
	v_and_b32_e32 v146, 0xffff0000, v151
	v_add3_u32 v153, v11, v153, s14
	s_waitcnt lgkmcnt(0)
	v_add_f32_e32 v69, v69, v147
	ds_bpermute_b32 v156, v179, v69
	v_and_b32_sdwa v154, v10, v203 dst_sel:DWORD dst_unused:UNUSED_PAD src0_sel:WORD_1 src1_sel:DWORD
	v_add3_u32 v152, v10, v154, s14
	v_and_b32_e32 v147, 0xffff0000, v155
	v_or_b32_sdwa v155, v147, v115 dst_sel:DWORD dst_unused:UNUSED_PAD src0_sel:DWORD src1_sel:WORD_1
	s_waitcnt lgkmcnt(0)
	v_add_f32_e32 v156, v69, v156
	ds_bpermute_b32 v157, v180, v156
	v_and_b32_e32 v69, 0xffff0000, v153
	v_or_b32_sdwa v154, v148, v150 dst_sel:DWORD dst_unused:UNUSED_PAD src0_sel:WORD_1 src1_sel:DWORD
	s_waitcnt lgkmcnt(0)
	v_add_f32_e32 v151, v156, v157
	v_fmamk_f32 v151, v151, 0x39800000, v204
	v_mul_f32_e32 v153, 0x4f800000, v151
	v_cmp_gt_f32_e32 vcc, s73, v151
	v_or_b32_sdwa v157, v69, v149 dst_sel:DWORD dst_unused:UNUSED_PAD src0_sel:DWORD src1_sel:WORD_1
	v_or_b32_sdwa v156, v152, v146 dst_sel:DWORD dst_unused:UNUSED_PAD src0_sel:WORD_1 src1_sel:DWORD
	v_cndmask_b32_e32 v151, v151, v153, vcc
	v_sqrt_f32_e32 v153, v151
	global_store_dwordx4 v[108:109], v[154:157], off offset:3072
	v_add_u32_e32 v108, -1, v153
	v_add_u32_e32 v109, 1, v153
	v_fma_f32 v154, -v108, v153, v151
	v_fma_f32 v155, -v109, v153, v151
	v_cmp_ge_f32_e64 s[44:45], 0, v154
	s_nop 1
	v_cndmask_b32_e64 v108, v153, v108, s[44:45]
	v_cmp_lt_f32_e64 s[44:45], 0, v155
	s_nop 1
	v_cndmask_b32_e64 v108, v108, v109, s[44:45]
	v_mul_f32_e32 v109, 0x37800000, v108
	v_cndmask_b32_e32 v108, v108, v109, vcc
	v_cmp_class_f32_e32 vcc, v151, v205
	s_nop 1
	v_cndmask_b32_e32 v108, v108, v151, vcc
	v_div_scale_f32 v109, s[10:11], v108, v108, 1.0
	v_rcp_f32_e32 v151, v109
	v_div_scale_f32 v153, vcc, 1.0, v108, 1.0
	v_fma_f32 v154, -v109, v151, 1.0
	v_fmac_f32_e32 v151, v154, v151
	v_mul_f32_e32 v154, v153, v151
	v_fma_f32 v155, -v109, v154, v153
	v_fmac_f32_e32 v154, v155, v151
	v_fma_f32 v109, -v109, v154, v153
	v_div_fmas_f32 v109, v109, v151, v154
	v_div_fixup_f32 v108, v109, v108, 1.0
	s_and_saveexec_b64 s[10:11], s[42:43]
	s_cbranch_execz .LBB0_646
	v_mov_b32_e32 v109, 0x120000
	global_store_dword v109, v108, s[8:9]
